# attention vector segment: LDS-DMA pieces spread over the whole segment (one every 9 VALU instead of every 3)
# baseline (speedup 1.0000x reference)
.Lattn_tb4:
	ds_read_b128 v[216:219], v187 offset:16384
	ds_read_b128 v[220:223], v187 offset:20480
	ds_read_b128 v[224:227], v187 offset:24576
	ds_read_b128 v[228:231], v187 offset:28672
	ds_read_b128 v[208:211], v188 offset:16384
	ds_read_b128 v[212:215], v188 offset:20480
	v_exp_f32_e32 v171, v96
	v_exp_f32_e32 v173, v97
	v_exp_f32_e32 v179, v98
	v_exp_f32_e32 v180, v99
	v_exp_f32_e32 v232, v100
	v_exp_f32_e32 v233, v101
	v_exp_f32_e32 v234, v102
	v_exp_f32_e32 v235, v103
	v_add_f32_e32 v190, v171, v173
	s_add_i32 m0, s5, 16384
	v_add_f32_e32 v191, v179, v180
	v_add_f32_e32 v190, v190, v232
	v_add_f32_e32 v191, v191, v233
	v_add_f32_e32 v190, v190, v234
	v_add_f32_e32 v191, v191, v235
	v_cvt_pk_bf16_f32 v144, v171, v173
	v_cvt_pk_bf16_f32 v145, v179, v180
	v_cvt_pk_bf16_f32 v146, v232, v233
	v_cvt_pk_bf16_f32 v147, v234, v235
	global_load_lds_dwordx4 v170, s[48:49]
	v_exp_f32_e32 v171, v104
	v_exp_f32_e32 v173, v105
	v_exp_f32_e32 v179, v106
	v_exp_f32_e32 v180, v107
	v_exp_f32_e32 v232, v108
	v_exp_f32_e32 v233, v109
	v_exp_f32_e32 v234, v110
	v_exp_f32_e32 v235, v111
	v_add_f32_e32 v190, v190, v171
	s_add_i32 m0, s5, 24576
	v_add_f32_e32 v191, v191, v173
	v_add_f32_e32 v190, v190, v179
	v_add_f32_e32 v191, v191, v180
	v_add_f32_e32 v190, v190, v232
	v_add_f32_e32 v191, v191, v233
	v_add_f32_e32 v190, v190, v234
	v_add_f32_e32 v191, v191, v235
	v_cvt_pk_bf16_f32 v148, v171, v173
	v_cvt_pk_bf16_f32 v149, v179, v180
	global_load_lds_dwordx4 v170, s[50:51]
	v_cvt_pk_bf16_f32 v150, v232, v233
	v_cvt_pk_bf16_f32 v151, v234, v235
	v_exp_f32_e32 v171, v112
	v_exp_f32_e32 v173, v113
	v_exp_f32_e32 v179, v114
	v_exp_f32_e32 v180, v115
	v_exp_f32_e32 v232, v116
	v_exp_f32_e32 v233, v117
	v_exp_f32_e32 v234, v118
	s_add_i32 m0, s5, 114688
	v_exp_f32_e32 v235, v119
	v_add_f32_e32 v190, v190, v171
	v_add_f32_e32 v191, v191, v173
	v_add_f32_e32 v190, v190, v179
	v_add_f32_e32 v191, v191, v180
	v_add_f32_e32 v190, v190, v232
	v_add_f32_e32 v191, v191, v233
	v_add_f32_e32 v190, v190, v234
	v_add_f32_e32 v191, v191, v235
	global_load_lds_dwordx4 v172, s[52:53]
	v_cvt_pk_bf16_f32 v152, v171, v173
	v_cvt_pk_bf16_f32 v153, v179, v180
	v_cvt_pk_bf16_f32 v154, v232, v233
	v_cvt_pk_bf16_f32 v155, v234, v235
	v_exp_f32_e32 v171, v120
	v_exp_f32_e32 v173, v121
	v_exp_f32_e32 v179, v122
	v_exp_f32_e32 v180, v123
	v_exp_f32_e32 v232, v124
	s_add_i32 m0, s5, 122880
	v_exp_f32_e32 v233, v125
	v_exp_f32_e32 v234, v126
	v_exp_f32_e32 v235, v127
	v_add_f32_e32 v190, v190, v171
	v_add_f32_e32 v191, v191, v173
	v_add_f32_e32 v190, v190, v179
	v_add_f32_e32 v191, v191, v180
	v_add_f32_e32 v190, v190, v232
	v_add_f32_e32 v191, v191, v233
	global_load_lds_dwordx4 v172, s[54:55]
	v_add_f32_e32 v190, v190, v234
	v_add_f32_e32 v191, v191, v235
	v_add_f32_e32 v190, v190, v191
	v_cmp_ngt_f32_e32 vcc, 0x71800000, v190
	v_cvt_pk_bf16_f32 v156, v171, v173
	v_cvt_pk_bf16_f32 v157, v179, v180
	v_cvt_pk_bf16_f32 v158, v232, v233
	v_cvt_pk_bf16_f32 v159, v234, v235
	s_nop 0
	s_cbranch_vccnz .Lattn_redo_L0
	v_add_f32_e32 v167, v167, v190
	s_cmp_lg_u32 s14, 0
	s_cbranch_scc1 .Lattn_tb5
	s_waitcnt vmcnt(4)
	s_barrier

.Lattn_tb6:
	ds_read_b128 v[216:219], v187 offset:32768
	ds_read_b128 v[220:223], v187 offset:36864
	ds_read_b128 v[224:227], v187 offset:40960
	ds_read_b128 v[228:231], v187 offset:45056
	ds_read_b128 v[208:211], v188 offset:32768
	ds_read_b128 v[212:215], v188 offset:36864
	v_exp_f32_e32 v171, v64
	v_exp_f32_e32 v173, v65
	v_exp_f32_e32 v179, v66
	v_exp_f32_e32 v180, v67
	v_exp_f32_e32 v232, v68
	v_exp_f32_e32 v233, v69
	v_exp_f32_e32 v234, v70
	v_exp_f32_e32 v235, v71
	v_add_f32_e32 v190, v171, v173
	s_add_i32 m0, s5, 32768
	v_add_f32_e32 v191, v179, v180
	v_add_f32_e32 v190, v190, v232
	v_add_f32_e32 v191, v191, v233
	v_add_f32_e32 v190, v190, v234
	v_add_f32_e32 v191, v191, v235
	v_cvt_pk_bf16_f32 v144, v171, v173
	v_cvt_pk_bf16_f32 v145, v179, v180
	v_cvt_pk_bf16_f32 v146, v232, v233
	v_cvt_pk_bf16_f32 v147, v234, v235
	global_load_lds_dwordx4 v170, s[48:49]
	v_exp_f32_e32 v171, v72
	v_exp_f32_e32 v173, v73
	v_exp_f32_e32 v179, v74
	v_exp_f32_e32 v180, v75
	v_exp_f32_e32 v232, v76
	v_exp_f32_e32 v233, v77
	v_exp_f32_e32 v234, v78
	v_exp_f32_e32 v235, v79
	v_add_f32_e32 v190, v190, v171
	s_add_i32 m0, s5, 40960
	v_add_f32_e32 v191, v191, v173
	v_add_f32_e32 v190, v190, v179
	v_add_f32_e32 v191, v191, v180
	v_add_f32_e32 v190, v190, v232
	v_add_f32_e32 v191, v191, v233
	v_add_f32_e32 v190, v190, v234
	v_add_f32_e32 v191, v191, v235
	v_cvt_pk_bf16_f32 v148, v171, v173
	v_cvt_pk_bf16_f32 v149, v179, v180
	global_load_lds_dwordx4 v170, s[50:51]
	v_cvt_pk_bf16_f32 v150, v232, v233
	v_cvt_pk_bf16_f32 v151, v234, v235
	v_exp_f32_e32 v171, v80
	v_exp_f32_e32 v173, v81
	v_exp_f32_e32 v179, v82
	v_exp_f32_e32 v180, v83
	v_exp_f32_e32 v232, v84
	v_exp_f32_e32 v233, v85
	v_exp_f32_e32 v234, v86
	s_add_i32 m0, s5, 65536
	v_exp_f32_e32 v235, v87
	v_add_f32_e32 v190, v190, v171
	v_add_f32_e32 v191, v191, v173
	v_add_f32_e32 v190, v190, v179
	v_add_f32_e32 v191, v191, v180
	v_add_f32_e32 v190, v190, v232
	v_add_f32_e32 v191, v191, v233
	v_add_f32_e32 v190, v190, v234
	v_add_f32_e32 v191, v191, v235
	global_load_lds_dwordx4 v172, s[52:53]
	v_cvt_pk_bf16_f32 v152, v171, v173
	v_cvt_pk_bf16_f32 v153, v179, v180
	v_cvt_pk_bf16_f32 v154, v232, v233
	v_cvt_pk_bf16_f32 v155, v234, v235
	v_exp_f32_e32 v171, v88
	v_exp_f32_e32 v173, v89
	v_exp_f32_e32 v179, v90
	v_exp_f32_e32 v180, v91
	v_exp_f32_e32 v232, v92
	s_add_i32 m0, s5, 73728
	v_exp_f32_e32 v233, v93
	v_exp_f32_e32 v234, v94
	v_exp_f32_e32 v235, v95
	v_add_f32_e32 v190, v190, v171
	v_add_f32_e32 v191, v191, v173
	v_add_f32_e32 v190, v190, v179
	v_add_f32_e32 v191, v191, v180
	v_add_f32_e32 v190, v190, v232
	v_add_f32_e32 v191, v191, v233
	global_load_lds_dwordx4 v172, s[54:55]
	v_add_f32_e32 v190, v190, v234
	v_add_f32_e32 v191, v191, v235
	v_add_f32_e32 v190, v190, v191
	v_cmp_ngt_f32_e32 vcc, 0x71800000, v190
	v_cvt_pk_bf16_f32 v156, v171, v173
	v_cvt_pk_bf16_f32 v157, v179, v180
	v_cvt_pk_bf16_f32 v158, v232, v233
	v_cvt_pk_bf16_f32 v159, v234, v235
	s_nop 0
	s_cbranch_vccnz .Lattn_redo_L1
	v_add_f32_e32 v167, v167, v190
	s_cmp_lg_u32 s14, 0
	s_cbranch_scc1 .Lattn_tb7
	s_waitcnt vmcnt(4)
	s_barrier

.Lattn_tb8:
	ds_read_b128 v[216:219], v187 offset:49152
	ds_read_b128 v[220:223], v187 offset:53248
	ds_read_b128 v[224:227], v187 offset:57344
	ds_read_b128 v[228:231], v187 offset:61440
	ds_read_b128 v[208:211], v188 offset:49152
	ds_read_b128 v[212:215], v188 offset:53248
	v_exp_f32_e32 v171, v96
	v_exp_f32_e32 v173, v97
	v_exp_f32_e32 v179, v98
	v_exp_f32_e32 v180, v99
	v_exp_f32_e32 v232, v100
	v_exp_f32_e32 v233, v101
	v_exp_f32_e32 v234, v102
	v_exp_f32_e32 v235, v103
	v_add_f32_e32 v190, v171, v173
	s_add_i32 m0, s5, 49152
	v_add_f32_e32 v191, v179, v180
	v_add_f32_e32 v190, v190, v232
	v_add_f32_e32 v191, v191, v233
	v_add_f32_e32 v190, v190, v234
	v_add_f32_e32 v191, v191, v235
	v_cvt_pk_bf16_f32 v144, v171, v173
	v_cvt_pk_bf16_f32 v145, v179, v180
	v_cvt_pk_bf16_f32 v146, v232, v233
	v_cvt_pk_bf16_f32 v147, v234, v235
	global_load_lds_dwordx4 v170, s[48:49]
	v_exp_f32_e32 v171, v104
	v_exp_f32_e32 v173, v105
	v_exp_f32_e32 v179, v106
	v_exp_f32_e32 v180, v107
	v_exp_f32_e32 v232, v108
	v_exp_f32_e32 v233, v109
	v_exp_f32_e32 v234, v110
	v_exp_f32_e32 v235, v111
	v_add_f32_e32 v190, v190, v171
	s_add_i32 m0, s5, 57344
	v_add_f32_e32 v191, v191, v173
	v_add_f32_e32 v190, v190, v179
	v_add_f32_e32 v191, v191, v180
	v_add_f32_e32 v190, v190, v232
	v_add_f32_e32 v191, v191, v233
	v_add_f32_e32 v190, v190, v234
	v_add_f32_e32 v191, v191, v235
	v_cvt_pk_bf16_f32 v148, v171, v173
	v_cvt_pk_bf16_f32 v149, v179, v180
	global_load_lds_dwordx4 v170, s[50:51]
	v_cvt_pk_bf16_f32 v150, v232, v233
	v_cvt_pk_bf16_f32 v151, v234, v235
	v_exp_f32_e32 v171, v112
	v_exp_f32_e32 v173, v113
	v_exp_f32_e32 v179, v114
	v_exp_f32_e32 v180, v115
	v_exp_f32_e32 v232, v116
	v_exp_f32_e32 v233, v117
	v_exp_f32_e32 v234, v118
	s_add_i32 m0, s5, 81920
	v_exp_f32_e32 v235, v119
	v_add_f32_e32 v190, v190, v171
	v_add_f32_e32 v191, v191, v173
	v_add_f32_e32 v190, v190, v179
	v_add_f32_e32 v191, v191, v180
	v_add_f32_e32 v190, v190, v232
	v_add_f32_e32 v191, v191, v233
	v_add_f32_e32 v190, v190, v234
	v_add_f32_e32 v191, v191, v235
	global_load_lds_dwordx4 v172, s[52:53]
	v_cvt_pk_bf16_f32 v152, v171, v173
	v_cvt_pk_bf16_f32 v153, v179, v180
	v_cvt_pk_bf16_f32 v154, v232, v233
	v_cvt_pk_bf16_f32 v155, v234, v235
	v_exp_f32_e32 v171, v120
	v_exp_f32_e32 v173, v121
	v_exp_f32_e32 v179, v122
	v_exp_f32_e32 v180, v123
	v_exp_f32_e32 v232, v124
	s_add_i32 m0, s5, 90112
	v_exp_f32_e32 v233, v125
	v_exp_f32_e32 v234, v126
	v_exp_f32_e32 v235, v127
	v_add_f32_e32 v190, v190, v171
	v_add_f32_e32 v191, v191, v173
	v_add_f32_e32 v190, v190, v179
	v_add_f32_e32 v191, v191, v180
	v_add_f32_e32 v190, v190, v232
	v_add_f32_e32 v191, v191, v233
	global_load_lds_dwordx4 v172, s[54:55]
	v_add_f32_e32 v190, v190, v234
	v_add_f32_e32 v191, v191, v235
	v_add_f32_e32 v190, v190, v191
	v_cmp_ngt_f32_e32 vcc, 0x71800000, v190
	v_cvt_pk_bf16_f32 v156, v171, v173
	v_cvt_pk_bf16_f32 v157, v179, v180
	v_cvt_pk_bf16_f32 v158, v232, v233
	v_cvt_pk_bf16_f32 v159, v234, v235
	s_nop 0
	s_cbranch_vccnz .Lattn_redo_L2
	v_add_f32_e32 v167, v167, v190
	s_cmp_lg_u32 s14, 0
	s_cbranch_scc1 .Lattn_tb9
	s_waitcnt vmcnt(4)
	s_barrier

.Lattn_tb10:
	ds_read_b128 v[216:219], v187 offset:0
	ds_read_b128 v[220:223], v187 offset:4096
	ds_read_b128 v[224:227], v187 offset:8192
	ds_read_b128 v[228:231], v187 offset:12288
	ds_read_b128 v[208:211], v188 offset:0
	ds_read_b128 v[212:215], v188 offset:4096
	v_exp_f32_e32 v171, v64
	v_exp_f32_e32 v173, v65
	v_exp_f32_e32 v179, v66
	v_exp_f32_e32 v180, v67
	v_exp_f32_e32 v232, v68
	v_exp_f32_e32 v233, v69
	v_exp_f32_e32 v234, v70
	v_exp_f32_e32 v235, v71
	v_add_f32_e32 v190, v171, v173
	s_add_i32 m0, s5, 0
	v_add_f32_e32 v191, v179, v180
	v_add_f32_e32 v190, v190, v232
	v_add_f32_e32 v191, v191, v233
	v_add_f32_e32 v190, v190, v234
	v_add_f32_e32 v191, v191, v235
	v_cvt_pk_bf16_f32 v144, v171, v173
	v_cvt_pk_bf16_f32 v145, v179, v180
	v_cvt_pk_bf16_f32 v146, v232, v233
	v_cvt_pk_bf16_f32 v147, v234, v235
	global_load_lds_dwordx4 v170, s[48:49]
	v_exp_f32_e32 v171, v72
	v_exp_f32_e32 v173, v73
	v_exp_f32_e32 v179, v74
	v_exp_f32_e32 v180, v75
	v_exp_f32_e32 v232, v76
	v_exp_f32_e32 v233, v77
	v_exp_f32_e32 v234, v78
	v_exp_f32_e32 v235, v79
	v_add_f32_e32 v190, v190, v171
	s_add_i32 m0, s5, 8192
	v_add_f32_e32 v191, v191, v173
	v_add_f32_e32 v190, v190, v179
	v_add_f32_e32 v191, v191, v180
	v_add_f32_e32 v190, v190, v232
	v_add_f32_e32 v191, v191, v233
	v_add_f32_e32 v190, v190, v234
	v_add_f32_e32 v191, v191, v235
	v_cvt_pk_bf16_f32 v148, v171, v173
	v_cvt_pk_bf16_f32 v149, v179, v180
	global_load_lds_dwordx4 v170, s[50:51]
	v_cvt_pk_bf16_f32 v150, v232, v233
	v_cvt_pk_bf16_f32 v151, v234, v235
	v_exp_f32_e32 v171, v80
	v_exp_f32_e32 v173, v81
	v_exp_f32_e32 v179, v82
	v_exp_f32_e32 v180, v83
	v_exp_f32_e32 v232, v84
	v_exp_f32_e32 v233, v85
	v_exp_f32_e32 v234, v86
	s_add_i32 m0, s5, 98304
	v_exp_f32_e32 v235, v87
	v_add_f32_e32 v190, v190, v171
	v_add_f32_e32 v191, v191, v173
	v_add_f32_e32 v190, v190, v179
	v_add_f32_e32 v191, v191, v180
	v_add_f32_e32 v190, v190, v232
	v_add_f32_e32 v191, v191, v233
	v_add_f32_e32 v190, v190, v234
	v_add_f32_e32 v191, v191, v235
	global_load_lds_dwordx4 v172, s[52:53]
	v_cvt_pk_bf16_f32 v152, v171, v173
	v_cvt_pk_bf16_f32 v153, v179, v180
	v_cvt_pk_bf16_f32 v154, v232, v233
	v_cvt_pk_bf16_f32 v155, v234, v235
	v_exp_f32_e32 v171, v88
	v_exp_f32_e32 v173, v89
	v_exp_f32_e32 v179, v90
	v_exp_f32_e32 v180, v91
	v_exp_f32_e32 v232, v92
	s_add_i32 m0, s5, 106496
	v_exp_f32_e32 v233, v93
	v_exp_f32_e32 v234, v94
	v_exp_f32_e32 v235, v95
	v_add_f32_e32 v190, v190, v171
	v_add_f32_e32 v191, v191, v173
	v_add_f32_e32 v190, v190, v179
	v_add_f32_e32 v191, v191, v180
	v_add_f32_e32 v190, v190, v232
	v_add_f32_e32 v191, v191, v233
	global_load_lds_dwordx4 v172, s[54:55]
	v_add_f32_e32 v190, v190, v234
	v_add_f32_e32 v191, v191, v235
	v_add_f32_e32 v190, v190, v191
	v_cmp_ngt_f32_e32 vcc, 0x71800000, v190
	v_cvt_pk_bf16_f32 v156, v171, v173
	v_cvt_pk_bf16_f32 v157, v179, v180
	v_cvt_pk_bf16_f32 v158, v232, v233
	v_cvt_pk_bf16_f32 v159, v234, v235
	s_nop 0
	s_cbranch_vccnz .Lattn_redo_L3
	v_add_f32_e32 v167, v167, v190
	s_add_i32 s42, s42, 4
	s_add_i32 s47, s47, -1
	s_cmp_lg_u32 s47, 0
	s_cbranch_scc1 .Lattn_loop_f
	s_cmp_lg_u32 s14, 0
	s_cbranch_scc1 .Lattn_tb11
	s_waitcnt vmcnt(4)
	s_barrier

.Lattn_tb12:
	ds_read_b128 v[216:219], v187 offset:16384
	ds_read_b128 v[220:223], v187 offset:20480
	ds_read_b128 v[224:227], v187 offset:24576
	ds_read_b128 v[228:231], v187 offset:28672
	ds_read_b128 v[208:211], v188 offset:16384
	ds_read_b128 v[212:215], v188 offset:20480
	v_exp_f32_e32 v171, v96
	v_exp_f32_e32 v173, v97
	v_exp_f32_e32 v179, v98
	v_exp_f32_e32 v180, v99
	v_exp_f32_e32 v232, v100
	v_exp_f32_e32 v233, v101
	v_exp_f32_e32 v234, v102
	v_exp_f32_e32 v235, v103
	v_add_f32_e32 v190, v171, v173
	s_add_i32 m0, s5, 114688
	v_add_f32_e32 v191, v179, v180
	v_add_f32_e32 v190, v190, v232
	v_add_f32_e32 v191, v191, v233
	v_add_f32_e32 v190, v190, v234
	v_add_f32_e32 v191, v191, v235
	v_cvt_pk_bf16_f32 v144, v171, v173
	v_cvt_pk_bf16_f32 v145, v179, v180
	v_cvt_pk_bf16_f32 v146, v232, v233
	v_cvt_pk_bf16_f32 v147, v234, v235
	global_load_lds_dwordx4 v172, s[52:53]
	v_exp_f32_e32 v171, v104
	v_exp_f32_e32 v173, v105
	v_exp_f32_e32 v179, v106
	v_exp_f32_e32 v180, v107
	v_exp_f32_e32 v232, v108
	v_exp_f32_e32 v233, v109
	v_exp_f32_e32 v234, v110
	v_exp_f32_e32 v235, v111
	v_add_f32_e32 v190, v190, v171
	s_add_i32 m0, s5, 122880
	v_add_f32_e32 v191, v191, v173
	v_add_f32_e32 v190, v190, v179
	v_add_f32_e32 v191, v191, v180
	v_add_f32_e32 v190, v190, v232
	v_add_f32_e32 v191, v191, v233
	v_add_f32_e32 v190, v190, v234
	v_add_f32_e32 v191, v191, v235
	v_cvt_pk_bf16_f32 v148, v171, v173
	v_cvt_pk_bf16_f32 v149, v179, v180
	global_load_lds_dwordx4 v172, s[54:55]
	v_cvt_pk_bf16_f32 v150, v232, v233
	v_cvt_pk_bf16_f32 v151, v234, v235
	v_exp_f32_e32 v171, v112
	v_exp_f32_e32 v173, v113
	v_exp_f32_e32 v179, v114
	v_exp_f32_e32 v180, v115
	v_exp_f32_e32 v232, v116
	v_exp_f32_e32 v233, v117
	v_exp_f32_e32 v234, v118
	v_exp_f32_e32 v235, v119
	v_add_f32_e32 v190, v190, v171
	v_add_f32_e32 v191, v191, v173
	v_add_f32_e32 v190, v190, v179
	v_add_f32_e32 v191, v191, v180
	v_add_f32_e32 v190, v190, v232
	v_add_f32_e32 v191, v191, v233
	v_add_f32_e32 v190, v190, v234
	v_add_f32_e32 v191, v191, v235
	v_cvt_pk_bf16_f32 v152, v171, v173
	v_cvt_pk_bf16_f32 v153, v179, v180
	v_cvt_pk_bf16_f32 v154, v232, v233
	v_cvt_pk_bf16_f32 v155, v234, v235
	v_exp_f32_e32 v171, v120
	v_exp_f32_e32 v173, v121
	v_exp_f32_e32 v179, v122
	v_exp_f32_e32 v180, v123
	v_exp_f32_e32 v232, v124
	v_exp_f32_e32 v233, v125
	v_exp_f32_e32 v234, v126
	v_exp_f32_e32 v235, v127
	v_add_f32_e32 v190, v190, v171
	v_add_f32_e32 v191, v191, v173
	v_add_f32_e32 v190, v190, v179
	v_add_f32_e32 v191, v191, v180
	v_add_f32_e32 v190, v190, v232
	v_add_f32_e32 v191, v191, v233
	v_add_f32_e32 v190, v190, v234
	v_add_f32_e32 v191, v191, v235
	v_add_f32_e32 v190, v190, v191
	v_cmp_ngt_f32_e32 vcc, 0x71800000, v190
	v_cvt_pk_bf16_f32 v156, v171, v173
	v_cvt_pk_bf16_f32 v157, v179, v180
	v_cvt_pk_bf16_f32 v158, v232, v233
	v_cvt_pk_bf16_f32 v159, v234, v235
	s_nop 0
	s_cbranch_vccnz .Lattn_redo_T29
	v_add_f32_e32 v167, v167, v190
	s_cmp_lg_u32 s14, 0
	s_cbranch_scc1 .Lattn_tb13
	s_waitcnt vmcnt(2)
	s_barrier
